# speedup vs baseline: 1.0067x; 1.0031x over previous
; #define LAS __attribute__((address_space(3)))
; #define GAS __attribute__((address_space(1)))
; #define ATT_KRD(KOFF, DLO, DHI) do { _Pragma("unroll") for (int d0 = (DLO); d0 < (DHI); ++d0) { kf[2 * d0] = *(const LAS bf16x8*)(lds + (KOFF) + kr + 2 * d0 * KCH); kf[2 * d0 + 1] = *(const LAS bf16x8*)(lds + (KOFF) + kr + 2 * d0 * KCH + 512); } } while (0)
; __device__ __forceinline__ void attn_unit(LAS unsigned char* lds, bf16_t* Qm, const bf16_t* __restrict__ Kb, const bf16_t* __restrict__ Vt,
;                                           int b, int h, int qb, int lgS, float lam, float oscale, const float* __restrict__ subg, float* stash) {
;     ...
;         const bf16_t* qp = Qm + (size_t)(tok0 + r32) * MIXW + (2 * h + c) * 64 + hi * 8;
;         bf16x8 qf[4];
; #pragma unroll
;         for (int d0 = 0; d0 < 4; ++d0) qf[d0] = *(const GAS bf16x8*)(qp + d0 * 16);
; #pragma unroll
;         for (int i = 0; i < 4; ++i)
; #pragma unroll
;             for (int r = 0; r < 16; ++r) o[i][r] = 0.f;
;         float mhat, lrun;
;         f32x16 negm;
; #pragma unroll
;         for (int r = 0; r < 16; ++r) negm[r] = 0.f;
;         const bf16_t* kg = Kb + (size_t)((b << lgS) + (tid >> 3)) * 512 + (2 * h + c) * 64 + (tid & 7) * 8;
;         const bf16_t* vg0 = Vt + ((size_t)(b * 512 + h * 128 + (tid >> 3)) << lgS) + (tid & 7) * 8;
;         const bf16_t* vg1 = vg0 + ((size_t)64 << lgS);
;         u32x4 kreg, vreg0, vreg1;
;         {
;             kreg = *(const GAS u32x4*)kg; vreg0 = *(const GAS u32x4*)vg0; vreg1 = *(const GAS u32x4*)vg1;
;             const u32x4 k1 = *(const GAS u32x4*)(kg + (size_t)64 * 512), k2 = *(const GAS u32x4*)(kg + (size_t)2 * 64 * 512), v10 = *(const GAS u32x4*)(vg0 + 64), v11 = *(const GAS u32x4*)(vg1 + 64);
;             *(LAS u32x4*)(lds + kw) = kreg; *(LAS u32x4*)(lds + vw0) = vreg0; *(LAS u32x4*)(lds + vw1) = vreg1;
;             *(LAS u32x4*)(lds + KBUF + kw) = k1; *(LAS u32x4*)(lds + VBUF + vw0) = v10; *(LAS u32x4*)(lds + VBUF + vw1) = v11;
;             *(LAS u32x4*)(lds + 2 * KBUF + kw) = k2;
;             kreg = *(const GAS u32x4*)(kg + (size_t)3 * 64 * 512); vreg0 = *(const GAS u32x4*)(vg0 + 2 * 64); vreg1 = *(const GAS u32x4*)(vg1 + 2 * 64);
;         }
;         __syncthreads();
;         u32x4 pk[4]; bf16x8 kf[8]; bf16x8 vfa[4], vfb[4];
;         {
;             f32x16 p0, p1;
;             ATT_KRD(0, 0, 4);
;             ATT_QK(p0, p1);
.LBB0_334:
	s_or_b32 s90, s25, s5
	s_lshl_b64 s[28:29], s[90:91], 1
	v_lshl_add_u64 v[12:13], v[228:229], 0, s[28:29]
	v_add_co_u32_e32 v4, vcc, 0x10000, v12
	v_lshl_add_u64 v[14:15], v[226:227], 0, s[28:29]
	s_nop 0
	v_addc_co_u32_e32 v5, vcc, 0, v13, vcc
	global_load_dwordx4 v[0:3], v[12:13], off
	s_nop 0
	global_load_dwordx4 v[4:7], v[4:5], off
	v_add_co_u32_e32 v8, vcc, 0x20000, v12
	v_add_u32_e32 v16, 0, v234
	s_nop 0
	v_addc_co_u32_e32 v9, vcc, 0, v13, vcc
	global_load_dwordx4 v[8:11], v[8:9], off
	s_nop 0
	global_load_dwordx4 v[136:139], v[14:15], off
	global_load_dwordx4 v[140:143], v[14:15], off offset:32
	global_load_dwordx4 v[144:147], v[14:15], off offset:64
	global_load_dwordx4 v[148:151], v[14:15], off offset:96
	v_add_co_u32_e32 v12, vcc, 0x30000, v12
	s_waitcnt vmcnt(8)
	v_mov_b64_e32 v[170:171], v[130:131]
	v_addc_co_u32_e32 v13, vcc, 0, v13, vcc
	global_load_dwordx4 v[152:155], v[12:13], off
	s_waitcnt vmcnt(8)
	v_mov_b64_e32 v[178:179], v[134:135]
	v_lshl_add_u64 v[238:239], v[236:237], 0, s[28:29]
	s_mov_b32 s56, 0x9000
	s_movk_i32 s50, 0x2100
	s_movk_i32 s29, 0x4200
	s_movk_i32 s25, 0x4800
	s_movk_i32 s90, 0xc0
	v_mov_b64_e32 v[168:169], v[128:129]
	v_mov_b64_e32 v[176:177], v[132:133]
	s_mov_b32 s28, 0
	s_mov_b32 s57, 0
	s_mov_b32 s60, 0
	s_waitcnt vmcnt(7)
	ds_write_b128 v248, v[0:3]
	ds_write_b128 v16, v[112:115] offset:25344
	ds_write_b128 v16, v[116:119] offset:34560
	s_waitcnt vmcnt(6)
	ds_write_b128 v248, v[4:7] offset:8448
	ds_write_b128 v16, v[120:123] offset:43776
	ds_write_b128 v16, v[124:127] offset:52992
	s_waitcnt vmcnt(5)
	ds_write_b128 v248, v[8:11] offset:16896
	s_waitcnt lgkmcnt(0)
	s_barrier
	ds_read_b128 v[0:3], v235
	ds_read_b128 v[18:21], v235 offset:512
	s_waitcnt vmcnt(4) lgkmcnt(1)
	v_mfma_f32_32x32x16_bf16 v[2:17], v[0:3], v[136:139], 0
	ds_read_b128 v[34:37], v235 offset:2112
	ds_read_b128 v[38:41], v235 offset:2624
	v_mov_b32_e32 v0, 0
	v_mov_b32_e32 v51, v0
	v_mov_b32_e32 v52, v0
	v_mov_b32_e32 v53, v0
	v_mov_b32_e32 v54, v0
	v_mov_b32_e32 v55, v0
	s_waitcnt lgkmcnt(2)
	v_mfma_f32_32x32x16_bf16 v[18:33], v[18:21], v[136:139], 0
	v_mov_b32_e32 v56, v0
	v_mov_b32_e32 v57, v0
	v_mov_b32_e32 v58, v0
	v_mov_b32_e32 v59, v0
	v_mov_b32_e32 v60, v0
	v_mov_b32_e32 v61, v0
	v_mov_b32_e32 v62, v0
	s_waitcnt vmcnt(3) lgkmcnt(1)
	v_mfma_f32_32x32x16_bf16 v[2:17], v[34:37], v[140:143], v[2:17]
	v_mov_b32_e32 v63, v0
	s_waitcnt lgkmcnt(0)
	v_mfma_f32_32x32x16_bf16 v[18:33], v[38:41], v[140:143], v[18:33]
	ds_read_b128 v[34:37], v235 offset:4224
	ds_read_b128 v[38:41], v235 offset:4736
	s_waitcnt vmcnt(2) lgkmcnt(1)
	v_mfma_f32_32x32x16_bf16 v[2:17], v[34:37], v[144:147], v[2:17]
	ds_read_b128 v[34:37], v235 offset:6336
	s_waitcnt lgkmcnt(1)
	v_mfma_f32_32x32x16_bf16 v[18:33], v[38:41], v[144:147], v[18:33]
	ds_read_b128 v[38:41], v235 offset:6848
	ds_read_b128 v[156:159], v235 offset:8448
	ds_read_b128 v[160:163], v235 offset:8960
	ds_read_b128 v[204:207], v235 offset:10560
	ds_read_b128 v[208:211], v235 offset:11072
	ds_read_b128 v[212:215], v235 offset:12672
	ds_read_b128 v[216:219], v235 offset:13184
	ds_read_b128 v[222:225], v235 offset:14784
	ds_read_b128 v[240:243], v235 offset:15296
	ds_read_b128 v[196:199], v220 offset:25344
	ds_read_b128 v[192:195], v220 offset:29952
	ds_read_b128 v[188:191], v220 offset:34560
	ds_read_b128 v[184:187], v220 offset:39168
	s_waitcnt lgkmcnt(0)
	s_barrier
; __device__ __forceinline__ void attn_unit(LAS unsigned char* lds, bf16_t* Qm, const bf16_t* __restrict__ Kb, const bf16_t* __restrict__ Vt,
;                                           int b, int h, int qb, int lgS, float lam, float oscale, const float* __restrict__ subg, float* stash) {
;     ...
;             float mx;
;             {
;                 float a_ = ATT_MX3(p0[0], p0[1], p1[0]), b_ = ATT_MX3(p0[2], p0[3], p1[1]); a_ = ATT_MX3(a_, p1[2], p1[3]);
; #pragma unroll
;                 for (int r = 4; r < 16; r += 4) { a_ = ATT_MX3(a_, p0[r], p0[r + 1]); b_ = ATT_MX3(b_, p0[r + 2], p0[r + 3]); a_ = ATT_MX3(a_, p1[r], p1[r + 1]); b_ = ATT_MX3(b_, p1[r + 2], p1[r + 3]); }
;                 const float m_ = __builtin_fmaxf(a_, b_);
;                 auto rr_ = __builtin_amdgcn_permlane32_swap(__float_as_uint(m_), __float_as_uint(m_), false, false);
;                 mx = __builtin_fmaxf(__uint_as_float(rr_[0]), __uint_as_float(rr_[1]));
;             }
;             mhat = mx;
; #pragma unroll
;             for (int r = 0; r < 16; ++r) negm[r] = -mx;
;             float sum = 0.f;
; #pragma unroll
;             for (int r = 0; r < 16; ++r) { p0[r] = __builtin_amdgcn_exp2f(p0[r] - mx); p1[r] = __builtin_amdgcn_exp2f(p1[r] - mx); sum += p0[r] + p1[r]; }
;             lrun = sum;
; #pragma unroll
;             for (int j = 0; j < 8; ++j) { pk[j >> 2][j & 3] = cvtpk_s(p0[2 * j], p0[2 * j + 1]); pk[2 + (j >> 2)][j & 3] = cvtpk_s(p1[2 * j], p1[2 * j + 1]); }
;             ATT_KRD(KBUF, 0, 1);
; #pragma unroll
;             for (int b2 = 0; b2 < 4; ++b2) vfa[b2] = *(const LAS bf16x8*)(lds + vr + b2 * 32 * VP);
;         }
;         __syncthreads();
;         int vs0 = 0, vs1 = VBUF, vs2 = 2 * VBUF;
;         int kq0 = 0, kq1 = KBUF, kq2 = 2 * KBUF;
; #pragma unroll 1
;         for (int t = 0; t < NT - 1; ++t) {
;             if (t + 3 < NT) *(LAS u32x4*)(lds + kq0 + kw) = kreg;
;             if (t + 2 < NT) { *(LAS u32x4*)(lds + vs2 + vw0) = vreg0; *(LAS u32x4*)(lds + vs2 + vw1) = vreg1; }
;             if (t + 4 < NT) kreg = *(const GAS u32x4*)(kg + (size_t)(t + 4) * 64 * 512);
;             if (t + 3 < NT) { vreg0 = *(const GAS u32x4*)(vg0 + (t + 3) * 64); vreg1 = *(const GAS u32x4*)(vg1 + (t + 3) * 64); }
;             f32x16 p0, p1;
;             ATT_KRD(kq1, 1, 4);
;             ATT_SB();
;             __builtin_amdgcn_s_setprio(1);
;             ATT_QK(p0, p1);
	s_waitcnt vmcnt(1)
	v_mfma_f32_32x32x16_bf16 v[2:17], v[34:37], v[148:151], v[2:17]
	v_mfma_f32_32x32x16_bf16 v[18:33], v[38:41], v[148:151], v[18:33]
	s_nop 10
	v_max_f32_e32 v1, v3, v3
	v_max_f32_e32 v34, v2, v2
	v_max_f32_e32 v1, v34, v1
	v_max3_f32 v35, v4, v5, v19
	v_max3_f32 v1, v1, v18, v20
	v_max3_f32 v34, v35, v8, v9
	v_max3_f32 v1, v1, v21, v6
	v_max3_f32 v34, v34, v24, v25
	v_max3_f32 v1, v1, v7, v22
	v_max3_f32 v34, v34, v12, v13
	v_max3_f32 v1, v1, v23, v10
	v_max3_f32 v34, v34, v28, v29
	v_max3_f32 v1, v1, v11, v26
	v_max3_f32 v34, v34, v16, v17
	v_max3_f32 v1, v1, v27, v14
	v_max3_f32 v34, v34, v32, v33
	v_max3_f32 v1, v1, v15, v30
	v_max3_f32 v1, v1, v31, v34
	v_mov_b32_e32 v34, v1
	s_nop 1
	v_permlane32_swap_b32_e32 v1, v34
	v_max_f32_e32 v34, v34, v34
	v_max_f32_e32 v1, v1, v1
	v_max_f32_e32 v250, v1, v34
	v_sub_f32_e32 v1, v26, v250
	v_sub_f32_e32 v26, v27, v250
	v_sub_f32_e32 v27, v28, v250
	v_sub_f32_e32 v28, v29, v250
	v_sub_f32_e32 v29, v30, v250
	v_sub_f32_e32 v30, v31, v250
	v_sub_f32_e32 v31, v32, v250
	v_sub_f32_e32 v41, v18, v250
	v_sub_f32_e32 v42, v19, v250
	v_sub_f32_e32 v47, v2, v250
	v_sub_f32_e32 v32, v33, v250
	v_sub_f32_e32 v36, v13, v250
	v_sub_f32_e32 v48, v3, v250
	v_sub_f32_e32 v49, v4, v250
	v_exp_f32_e32 v3, v1
	v_exp_f32_e32 v4, v28
	v_exp_f32_e32 v13, v31
	v_exp_f32_e32 v1, v41
	v_exp_f32_e32 v28, v42
	v_exp_f32_e32 v31, v47
	v_sub_f32_e32 v33, v10, v250
	v_sub_f32_e32 v35, v12, v250
	v_sub_f32_e32 v43, v20, v250
	v_exp_f32_e32 v12, v32
	v_exp_f32_e32 v32, v48
	v_sub_f32_e32 v34, v11, v250
	v_sub_f32_e32 v38, v15, v250
	v_sub_f32_e32 v44, v21, v250
	v_sub_f32_e32 v50, v5, v250
	v_exp_f32_e32 v11, v29
	v_exp_f32_e32 v15, v33
	v_exp_f32_e32 v29, v43
	v_exp_f32_e32 v33, v49
	v_sub_f32_e32 v37, v14, v250
	v_sub_f32_e32 v22, v22, v250
	v_sub_f32_e32 v45, v23, v250
	v_exp_f32_e32 v10, v30
	v_exp_f32_e32 v14, v34
	v_exp_f32_e32 v30, v44
	v_exp_f32_e32 v34, v50
	v_sub_f32_e32 v6, v6, v250
	v_exp_f32_e32 v5, v27
	v_exp_f32_e32 v23, v22
	v_exp_f32_e32 v22, v45
	v_cvt_pk_bf16_f32 v172, v1, v28
	v_exp_f32_e32 v27, v6
	v_sub_f32_e32 v6, v7, v250
	v_add_f32_e32 v1, v1, v31
	v_exp_f32_e32 v2, v26
	v_exp_f32_e32 v26, v6
	v_sub_f32_e32 v6, v8, v250
	v_add_f32_e32 v1, 0, v1
	v_add_f32_e32 v8, v28, v32
	v_add_f32_e32 v1, v8, v1
	v_add_f32_e32 v8, v29, v33
	v_sub_f32_e32 v24, v24, v250
	v_sub_f32_e32 v46, v25, v250
	v_add_f32_e32 v1, v8, v1
	v_add_f32_e32 v8, v30, v34
	v_exp_f32_e32 v25, v24
	v_exp_f32_e32 v24, v46
	v_exp_f32_e32 v7, v6
	v_sub_f32_e32 v6, v9, v250
	v_add_f32_e32 v1, v8, v1
	v_pk_mov_b32 v[8:9], v[22:23], v[22:23] op_sel:[1,0]
	v_exp_f32_e32 v6, v6
	v_cvt_pk_bf16_f32 v174, v8, v9
	v_pk_mov_b32 v[8:9], v[26:27], v[26:27] op_sel:[1,0]
	v_sub_f32_e32 v39, v16, v250
	v_cvt_pk_bf16_f32 v202, v8, v9
	v_pk_add_f32 v[8:9], v[22:23], v[26:27]
	v_sub_f32_e32 v40, v17, v250
	v_add_f32_e32 v1, v9, v1
	v_add_f32_e32 v1, v8, v1
	v_pk_mov_b32 v[8:9], v[24:25], v[24:25] op_sel:[1,0]
	v_exp_f32_e32 v17, v35
	v_cvt_pk_bf16_f32 v175, v8, v9
	v_pk_mov_b32 v[8:9], v[6:7], v[6:7] op_sel:[1,0]
	v_pk_add_f32 v[6:7], v[24:25], v[6:7]
	v_exp_f32_e32 v16, v36
	v_add_f32_e32 v1, v7, v1
	v_add_f32_e32 v1, v6, v1
	v_pk_mov_b32 v[6:7], v[2:3], v[2:3] op_sel:[1,0]
	v_pk_add_f32 v[2:3], v[2:3], v[14:15]
	v_exp_f32_e32 v19, v37
	v_add_f32_e32 v1, v3, v1
	v_add_f32_e32 v1, v2, v1
	v_pk_mov_b32 v[2:3], v[4:5], v[4:5] op_sel:[1,0]
	v_exp_f32_e32 v18, v38
	v_cvt_pk_bf16_f32 v165, v2, v3
	v_pk_mov_b32 v[2:3], v[16:17], v[16:17] op_sel:[1,0]
	v_exp_f32_e32 v21, v39
	v_cvt_pk_bf16_f32 v181, v2, v3
	v_pk_add_f32 v[2:3], v[4:5], v[16:17]
	v_exp_f32_e32 v20, v40
	v_add_f32_e32 v1, v3, v1
	v_add_f32_e32 v1, v2, v1
	v_pk_mov_b32 v[2:3], v[10:11], v[10:11] op_sel:[1,0]
	v_xor_b32_e32 v64, 0x80000000, v250
	v_cvt_pk_bf16_f32 v166, v2, v3
	v_pk_mov_b32 v[2:3], v[18:19], v[18:19] op_sel:[1,0]
	v_cvt_pk_bf16_f32 v164, v6, v7
	v_cvt_pk_bf16_f32 v182, v2, v3
	v_pk_add_f32 v[2:3], v[10:11], v[18:19]
	v_pk_mov_b32 v[6:7], v[14:15], v[14:15] op_sel:[1,0]
	v_add_f32_e32 v1, v3, v1
	v_add_f32_e32 v1, v2, v1
	v_pk_mov_b32 v[2:3], v[12:13], v[12:13] op_sel:[1,0]
	v_cvt_pk_bf16_f32 v173, v29, v30
	v_cvt_pk_bf16_f32 v167, v2, v3
	v_pk_mov_b32 v[2:3], v[20:21], v[20:21] op_sel:[1,0]
	v_cvt_pk_bf16_f32 v200, v31, v32
	v_cvt_pk_bf16_f32 v183, v2, v3
	v_pk_add_f32 v[2:3], v[12:13], v[20:21]
	v_cvt_pk_bf16_f32 v201, v33, v34
	v_add_f32_e32 v1, v3, v1
	v_cvt_pk_bf16_f32 v203, v8, v9
	v_cvt_pk_bf16_f32 v180, v6, v7
	v_add_f32_e32 v249, v2, v1
	v_mov_b32_e32 v1, v0
	v_mov_b32_e32 v2, v0
	v_mov_b32_e32 v3, v0
	v_mov_b32_e32 v4, v0
	v_mov_b32_e32 v5, v0
	v_mov_b32_e32 v6, v0
	v_mov_b32_e32 v7, v0
	v_mov_b32_e32 v8, v0
	v_mov_b32_e32 v9, v0
	v_mov_b32_e32 v10, v0
	v_mov_b32_e32 v11, v0
	v_mov_b32_e32 v12, v0
	v_mov_b32_e32 v13, v0
	v_mov_b32_e32 v14, v0
	v_mov_b32_e32 v15, v0
	v_mov_b32_e32 v48, v0
	v_mov_b32_e32 v49, v0
	v_mov_b32_e32 v50, v0
	v_mov_b32_e32 v32, v0
	v_mov_b32_e32 v33, v0
	v_mov_b32_e32 v34, v0
	v_mov_b32_e32 v35, v0
	v_mov_b32_e32 v36, v0
	v_mov_b32_e32 v37, v0
	v_mov_b32_e32 v38, v0
	v_mov_b32_e32 v39, v0
	v_mov_b32_e32 v40, v0
	v_mov_b32_e32 v41, v0
	v_mov_b32_e32 v42, v0
	v_mov_b32_e32 v43, v0
	v_mov_b32_e32 v44, v0
	v_mov_b32_e32 v45, v0
	v_mov_b32_e32 v46, v0
	v_mov_b32_e32 v47, v0
	v_mov_b32_e32 v16, v0
	v_mov_b32_e32 v17, v0
	v_mov_b32_e32 v18, v0
	v_mov_b32_e32 v19, v0
	v_mov_b32_e32 v20, v0
	v_mov_b32_e32 v21, v0
	v_mov_b32_e32 v22, v0
	v_mov_b32_e32 v23, v0
	v_mov_b32_e32 v24, v0
	v_mov_b32_e32 v25, v0
	v_mov_b32_e32 v26, v0
	v_mov_b32_e32 v27, v0
	v_mov_b32_e32 v28, v0
	v_mov_b32_e32 v29, v0
	v_mov_b32_e32 v30, v0
	v_mov_b32_e32 v31, v0
	v_mov_b32_e32 v65, v64
	v_mov_b32_e32 v66, v64
	v_mov_b32_e32 v67, v64
	v_mov_b32_e32 v68, v64
	v_mov_b32_e32 v69, v64
	v_mov_b32_e32 v70, v64
	v_mov_b32_e32 v71, v64
	v_mov_b32_e32 v72, v64
	v_mov_b32_e32 v73, v64
	v_mov_b32_e32 v74, v64
	v_mov_b32_e32 v75, v64
	v_mov_b32_e32 v76, v64
	v_mov_b32_e32 v77, v64
	v_mov_b32_e32 v78, v64
	v_mov_b32_e32 v79, v64
	s_cmp_eq_u32 s98, 0
	s_cbranch_scc1 .Lmy_noprio
	s_setprio 1
.Lmy_noprio:
.LBB0_335:
	s_mov_b32 s61, s50
	s_mov_b32 s50, s29
	s_mov_b32 s65, s28
	v_mfma_f32_32x32x16_bf16 v[96:111], v[156:159], v[136:139], v[64:79]
	v_mfma_f32_32x32x16_bf16 v[80:95], v[160:163], v[136:139], v[64:79]
	s_add_i32 s29, s57, 3
	s_cmp_lt_u32 s29, s38
	s_cselect_b64 s[30:31], -1, 0
	s_cmp_ge_u32 s29, s38
	s_cbranch_scc1 .Lmy_skip_kw
	v_add_u32_e32 v156, s60, v248
	s_waitcnt vmcnt(0)
	ds_write_b128 v156, v[152:155]

; #define LAS __attribute__((address_space(3)))
; #define GAS __attribute__((address_space(1)))
; __device__ __forceinline__ void attn_unit(LAS unsigned char* lds, bf16_t* Qm, const bf16_t* __restrict__ Kb, const bf16_t* __restrict__ Vt,
;                                           int b, int h, int qb, int lgS, float lam, float oscale, const float* __restrict__ subg, float* stash) {
;     ...
;         const bf16_t* qp = Qm + (size_t)(tok0 + r32) * MIXW + (2 * h + c) * 64 + hi * 8;
;         bf16x8 qf[4];
; #pragma unroll
;         for (int d0 = 0; d0 < 4; ++d0) qf[d0] = *(const GAS bf16x8*)(qp + d0 * 16);
; #pragma unroll
;         for (int i = 0; i < 4; ++i)
; #pragma unroll
;             for (int r = 0; r < 16; ++r) o[i][r] = 0.f;
;         float mhat, lrun;
;         f32x16 negm;
; #pragma unroll
;         for (int r = 0; r < 16; ++r) negm[r] = 0.f;
;         const bf16_t* kg = Kb + (size_t)((b << lgS) + (tid >> 3)) * 512 + (2 * h + c) * 64 + (tid & 7) * 8;
;         const bf16_t* vg0 = Vt + ((size_t)(b * 512 + h * 128 + (tid >> 3)) << lgS) + (tid & 7) * 8;
;         const bf16_t* vg1 = vg0 + ((size_t)64 << lgS);
;         u32x4 kreg, vreg0, vreg1;
;         {
;             kreg = *(const GAS u32x4*)kg; vreg0 = *(const GAS u32x4*)vg0; vreg1 = *(const GAS u32x4*)vg1;
;             const u32x4 k1 = *(const GAS u32x4*)(kg + (size_t)64 * 512), k2 = *(const GAS u32x4*)(kg + (size_t)2 * 64 * 512), v10 = *(const GAS u32x4*)(vg0 + 64), v11 = *(const GAS u32x4*)(vg1 + 64);
;             *(LAS u32x4*)(lds + kw) = kreg; *(LAS u32x4*)(lds + vw0) = vreg0; *(LAS u32x4*)(lds + vw1) = vreg1;
;             *(LAS u32x4*)(lds + KBUF + kw) = k1; *(LAS u32x4*)(lds + VBUF + vw0) = v10; *(LAS u32x4*)(lds + VBUF + vw1) = v11;
;             *(LAS u32x4*)(lds + 2 * KBUF + kw) = k2;
;             kreg = *(const GAS u32x4*)(kg + (size_t)3 * 64 * 512); vreg0 = *(const GAS u32x4*)(vg0 + 2 * 64); vreg1 = *(const GAS u32x4*)(vg1 + 2 * 64);
;     ...
;             __builtin_amdgcn_s_setprio(1);
;             ATT_QK(p0, p1);
;             __builtin_amdgcn_s_setprio(0);
.LBB0_349:
	s_setprio 0
	s_and_b64 vcc, exec, s[26:27]
	s_cbranch_vccz .Lmy_skip_pf
	s_mov_b32 m0, 0x18000
	s_lshl_b32 s100, s5, 1
	s_add_u32 s100, s100, 0x80
	s_mov_b32 s101, 0
	v_lshl_add_u64 v[84:85], v[226:227], 0, s[100:101]
	global_load_lds_dword v[84:85], off
	s_lshl_b32 s100, s5, 1
	s_add_u32 s100, s100, 0x80
	v_lshl_add_u64 v[86:87], v[228:229], 0, s[100:101]
	global_load_lds_dword v[86:87], off
	s_add_u32 s100, s100, 0x10000
	v_lshl_add_u64 v[88:89], v[228:229], 0, s[100:101]
	global_load_lds_dword v[88:89], off
	s_add_u32 s100, s100, 0x10000
	v_lshl_add_u64 v[90:91], v[228:229], 0, s[100:101]
	global_load_lds_dword v[90:91], off
	s_add_u32 s100, s100, 0x10000
	v_lshl_add_u64 v[92:93], v[228:229], 0, s[100:101]
	global_load_lds_dword v[92:93], off
